# scan: each thread stages 8 consecutive dk so k/q/b/b_last loads are single dwordx4 (9 loads per thread-step instead of 16); sQt/sKt written as two ds_write_b64 halves
# speedup vs baseline: 1.0327x; 1.0004x over previous
.LBB0_1144:
	s_ashr_i32 s5, s85, 2
	s_lshl_b32 s7, s85, 6
	s_lshl_b32 s6, s5, 8
	s_and_b32 s10, s7, 0x80
	s_or_b32 s6, s6, s10
	s_and_b32 s4, s85, 1
	s_bfe_i32 s8, s85, 0x10000
	s_ashr_i32 s12, s85, 4
	s_mul_hi_i32 s7, s6, 0x4200
	s_mulk_i32 s6, 0x4200
	s_and_b32 s11, s5, 3
	s_add_u32 s6, s56, s6
	s_addc_u32 s7, s57, s7
	s_cmp_eq_u32 s4, 0
	s_cselect_b64 s[4:5], -1, 0
	v_mov_b32_e32 v3, v148
	s_and_b64 s[14:15], s[4:5], exec
	s_mov_b32 s9, 0xc400000
	s_barrier
	s_cselect_b32 s9, s9, 0x10600000
	v_ashrrev_i32_e32 v14, 6, v3
	s_mov_b32 s13, 0x14800000
	v_add_u32_e32 v0, -4, v14
	s_cselect_b32 s13, s13, 0x1c800000
	s_cselect_b32 s86, 63, 0
	s_add_u32 s70, s54, s9
	v_lshrrev_b32_e32 v15, 1, v0
	v_and_b32_e32 v16, 1, v14
	s_addc_u32 s71, s55, 0
	v_cmp_gt_u32_e32 vcc, v16, v15
	s_add_u32 s13, s54, s13
	s_addc_u32 s14, s55, 0
	v_cndmask_b32_e64 v0, 0, 1, vcc
	v_cmp_lt_u32_e32 vcc, v16, v15
	s_lshl_b32 s87, s12, 8
	s_and_b32 s8, s8, 0xc0
	v_cndmask_b32_e64 v4, 0, 1, vcc
	s_add_i32 s87, s87, 0x10000
	v_cndmask_b32_e64 v17, v4, v0, s[4:5]
	s_or_b32 s15, s87, s8
	v_lshlrev_b32_e32 v4, 2, v3
	s_lshl_b32 s16, s8, 1
	s_or_b32 s8, s15, s86
	v_ashrrev_i32_e32 v149, 4, v3
	v_lshlrev_b32_e32 v0, 3, v3
	v_and_b32_e32 v21, 4, v4
	s_ashr_i32 s9, s8, 31
	v_and_b32_e32 v22, 0x78, v0
	v_add_u32_e32 v4, s15, v149
	v_ashrrev_i32_e32 v5, 31, v4
	v_lshl_or_b32 v136, s11, 7, v22
	s_lshl_b64 s[8:9], s[8:9], 10
	v_lshlrev_b64 v[4:5], 10, v[4:5]
	s_waitcnt vmcnt(11)
	v_lshlrev_b32_e32 v8, 1, v136
	s_add_u32 s8, s70, s8
	v_or_b32_e32 v4, v4, v8
	s_addc_u32 s9, s71, s9
	s_lshl_b32 s17, s11, 8
	v_add_u32_e32 v23, 0x200, v3
	s_waitcnt vmcnt(5)
	v_lshl_add_u64 v[6:7], s[76:77], 0, v[4:5]
	s_add_u32 s8, s8, s17
	v_ashrrev_i32_e32 v172, 4, v23
	s_addc_u32 s9, s9, 0
	v_lshlrev_b32_e32 v0, 1, v22
	global_load_dwordx4 v[138:141], v[6:7], off
	global_load_dwordx4 v[142:145], v0, s[8:9]
	v_add_u32_e32 v6, s15, v172
	v_ashrrev_i32_e32 v7, 31, v6
	v_lshlrev_b64 v[6:7], 10, v[6:7]
	v_lshl_add_u64 v[4:5], s[70:71], 0, v[4:5]
	v_or_b32_e32 v6, v6, v8
	v_lshl_add_u64 v[8:9], s[76:77], 0, v[6:7]
	global_load_dwordx4 v[156:159], v[4:5], off
	global_load_dwordx4 v[160:163], v[8:9], off
	v_lshl_add_u64 v[4:5], s[70:71], 0, v[6:7]
	global_load_dwordx4 v[164:167], v[4:5], off
	v_ashrrev_i32_e32 v12, 3, v3
	v_mov_b64_e32 v[4:5], s[6:7]
	v_mad_i64_i32 v[6:7], s[6:7], v12, s33, v[4:5]
	v_add_u32_e32 v12, 64, v12
	s_or_b32 s48, s16, 0x4000
	v_lshlrev_b32_e32 v24, 4, v3
	v_mad_i64_i32 v[4:5], s[6:7], v12, s33, v[4:5]
	v_lshl_add_u64 v[8:9], v[6:7], 0, s[48:49]
	v_and_b32_e32 v10, 0x70, v24
	v_mov_b32_e32 v11, v1
	v_lshl_add_u64 v[12:13], v[4:5], 0, s[48:49]
	v_lshl_add_u64 v[8:9], v[8:9], 0, v[10:11]
	v_lshl_add_u64 v[12:13], v[12:13], 0, v[10:11]
	global_load_dwordx4 v[128:131], v[8:9], off
	global_load_dwordx4 v[132:135], v[12:13], off
	v_ashrrev_i32_e32 v8, 7, v3
	v_lshlrev_b32_e32 v9, 1, v149
	v_lshrrev_b32_e32 v12, 1, v21
	v_and_b32_e32 v25, 14, v9
	v_lshlrev_b32_e32 v9, 7, v22
	v_xor_b32_e32 v13, v12, v8
	v_lshl_add_u32 v26, v13, 4, v9
	v_or_b32_e32 v13, 2, v22
	v_or_b32_e32 v29, 3, v22
	v_or_b32_e32 v32, 8, v22
	v_or_b32_e32 v35, 9, v22
	v_or_b32_e32 v38, 10, v22
	v_or_b32_e32 v22, 11, v22
	v_lshlrev_b32_e32 v27, 7, v13
	v_lshrrev_b32_e32 v13, 1, v13
	v_lshlrev_b32_e32 v30, 7, v29
	v_lshrrev_b32_e32 v29, 1, v29
	v_lshlrev_b32_e32 v33, 7, v32
	v_lshrrev_b32_e32 v32, 1, v32
	v_lshlrev_b32_e32 v36, 7, v35
	v_lshrrev_b32_e32 v35, 1, v35
	v_lshlrev_b32_e32 v39, 7, v38
	v_lshrrev_b32_e32 v38, 1, v38
	v_lshlrev_b32_e32 v41, 7, v22
	v_lshrrev_b32_e32 v22, 1, v22
	v_bitop3_b32 v28, v13, v8, 3 bitop3:0x6c
	v_bitop3_b32 v31, v29, v8, 3 bitop3:0x6c
	v_bitop3_b32 v34, v32, v8, 6 bitop3:0x6c
	v_bitop3_b32 v37, v35, v8, 6 bitop3:0x6c
	v_bitop3_b32 v40, v38, v8, 7 bitop3:0x6c
	v_bitop3_b32 v8, v22, v8, 7 bitop3:0x6c
	v_xor_b32_e32 v43, v149, v3
	v_lshl_add_u32 v42, v8, 4, v41
	v_lshlrev_b32_e32 v8, 8, v149
	v_lshlrev_b32_e32 v43, 4, v43
	s_add_u32 s8, s70, s17
	v_and_or_b32 v173, v43, s84, v8
	v_ashrrev_i32_e32 v8, 7, v23
	s_addc_u32 s9, s71, 0
	v_lshl_add_u64 v[154:155], v[4:5], 0, v[10:11]
	s_lshl_b32 s88, s12, 13
	v_lshlrev_b32_e32 v4, 5, v3
	v_lshlrev_b32_e32 v5, 2, v21
	s_movk_i32 s12, 0xffc0
	v_xor_b32_e32 v12, v12, v8
	s_nop 0
	v_lshl_add_u32 v43, v12, 4, v9
	v_bitop3_b32 v9, v13, v8, 3 bitop3:0x6c
	v_add_u32_e32 v176, 0x16000, v4
	v_and_b32_e32 v4, 1, v17
	v_lshl_add_u32 v28, v28, 4, v27
	v_lshl_add_u32 v27, v9, 4, v27
	v_bitop3_b32 v9, v29, v8, 3 bitop3:0x6c
	v_cmp_eq_u32_e32 vcc, 1, v4
	v_lshl_add_u32 v29, v9, 4, v30
	v_bitop3_b32 v9, v32, v8, 6 bitop3:0x6c
	s_xor_b64 s[78:79], vcc, -1
	s_lshl_b32 s11, s11, 9
	v_lshl_add_u32 v31, v31, 4, v30
	v_lshl_add_u32 v30, v9, 4, v33
	v_bitop3_b32 v9, v35, v8, 6 bitop3:0x6c
	s_add_u32 s11, s13, s11
	v_and_b32_e32 v18, 31, v3
	v_lshl_add_u32 v32, v9, 4, v36
	v_bitop3_b32 v9, v38, v8, 7 bitop3:0x6c
	v_lshl_add_u64 v[146:147], s[8:9], 0, v[0:1]
	v_lshlrev_b32_e32 v0, 5, v14
	s_addc_u32 s12, s14, 0
	s_lshl_b32 s10, s10, 1
	v_lshrrev_b32_e32 v2, 5, v3
	v_bfe_u32 v19, v3, 5, 1
	v_bfe_u32 v20, v3, 1, 3
	v_lshl_add_u32 v34, v34, 4, v33
	v_lshl_add_u32 v33, v9, 4, v39
	v_xor_b32_e32 v9, v172, v3
	v_and_b32_e32 v35, 0xffffff80, v24
	v_bitop3_b32 v24, v24, s51, v3 bitop3:0x48
	v_cmp_gt_i32_e64 s[6:7], 16, v3
	v_lshl_add_u64 v[152:153], v[6:7], 0, v[10:11]
	v_and_b32_e32 v0, 0x60, v0
	v_lshlrev_b32_e32 v177, 8, v18
	v_and_b32_e32 v6, 15, v3
	v_lshlrev_b32_e32 v3, 1, v3
	s_add_u32 s10, s11, s10
	v_lshl_or_b32 v179, v16, 13, v177
	v_lshl_or_b32 v7, v16, 5, v18
	v_and_b32_e32 v16, 14, v3
	v_or_b32_e32 v3, v0, v18
	s_addc_u32 s11, s12, 0
	v_lshlrev_b32_e32 v0, 1, v0
	v_lshl_add_u64 v[4:5], s[10:11], 0, v[0:1]
	v_lshlrev_b32_e32 v0, 1, v18
	v_lshl_add_u64 v[4:5], v[4:5], 0, v[0:1]
	v_bitop3_b32 v0, v2, v6, 1 bitop3:0x6c
	v_lshlrev_b32_e32 v184, 4, v0
	v_bitop3_b32 v0, v19, v6, 2 bitop3:0x36
	v_lshlrev_b32_e32 v185, 4, v0
	v_bitop3_b32 v0, v19, v6, 4 bitop3:0x36
	v_lshlrev_b32_e32 v186, 4, v0
	v_bitop3_b32 v0, v19, v6, 6 bitop3:0x36
	v_lshlrev_b32_e32 v187, 4, v0
	v_bitop3_b32 v0, v19, v6, 8 bitop3:0x36
	v_bitop3_b32 v8, v22, v8, 7 bitop3:0x6c
	v_lshlrev_b32_e32 v188, 4, v0
	v_bitop3_b32 v0, v19, v6, 10 bitop3:0x36
	v_lshl_add_u32 v22, v8, 4, v41
	v_lshlrev_b32_e32 v8, 8, v172
	v_lshlrev_b32_e32 v9, 4, v9
	v_lshlrev_b32_e32 v189, 4, v0
	v_bitop3_b32 v0, v19, v6, 12 bitop3:0x36
	v_and_or_b32 v174, v9, s84, v8
	v_lshlrev_b32_e32 v8, 2, v19
	v_lshlrev_b32_e32 v190, 4, v0
	v_bitop3_b32 v0, v19, v6, 14 bitop3:0x36
	v_lshlrev_b32_e32 v191, 4, v0
	v_lshl_or_b32 v0, v15, 5, v8
	v_cmp_le_u32_e32 vcc, v7, v0
	v_lshlrev_b32_e32 v180, 7, v3
	v_lshrrev_b32_e32 v9, 3, v7
	v_cndmask_b32_e64 v3, 0, 1, vcc
	v_cmp_ge_u32_e32 vcc, v7, v0
	v_lshlrev_b32_e32 v8, 4, v9
	v_lshlrev_b32_e32 v181, 7, v18
	v_cndmask_b32_e64 v6, 0, 1, vcc
	v_cndmask_b32_e64 v3, v6, v3, s[4:5]
	v_and_b32_e32 v3, 1, v3
	v_cmp_eq_u32_e64 s[10:11], 1, v3
	v_lshlrev_b32_e32 v3, 7, v0
	v_lshlrev_b32_e32 v6, 5, v19
	v_bitop3_b32 v3, v3, v8, v6 bitop3:0xf6
	v_add_u32_e32 v17, 0x14000, v3
	v_or_b32_e32 v3, 1, v0
	v_cmp_gt_u32_e32 vcc, v7, v0
	v_lshl_add_u32 v37, v37, 4, v36
	v_lshl_add_u32 v40, v40, 4, v39
	v_cndmask_b32_e64 v10, 0, 1, vcc
	v_cmp_le_u32_e32 vcc, v7, v3
	v_lshlrev_b32_e32 v3, 7, v3
	v_bitop3_b32 v3, v3, v8, v6 bitop3:0xf6
	v_cndmask_b32_e64 v11, 0, 1, vcc
	v_cndmask_b32_e64 v10, v10, v11, s[4:5]
	v_add_u32_e32 v18, 0x14000, v3
	v_or_b32_e32 v3, 2, v0
	v_and_b32_e32 v10, 1, v10
	v_cmp_le_u32_e32 vcc, v7, v3
	v_cmp_eq_u32_e64 s[12:13], 1, v10
	v_lshlrev_b32_e32 v23, 1, v172
	v_cndmask_b32_e64 v10, 0, 1, vcc
	v_cmp_ge_u32_e32 vcc, v7, v3
	v_and_b32_e32 v23, 14, v23
	v_cmp_gt_i32_e64 s[8:9], 4, v14
	v_cndmask_b32_e64 v11, 0, 1, vcc
	v_cndmask_b32_e64 v10, v11, v10, s[4:5]
	v_and_b32_e32 v10, 1, v10
	v_cmp_eq_u32_e64 s[14:15], 1, v10
	v_lshrrev_b32_e32 v10, 1, v3
	v_bitop3_b32 v10, v10, v9, 3 bitop3:0x6c
	v_lshlrev_b32_e32 v10, 4, v10
	v_lshl_or_b32 v3, v3, 7, v10
	v_add_u32_e32 v21, 0x14000, v3
	v_or_b32_e32 v3, 3, v0
	v_cmp_le_u32_e32 vcc, v7, v3
	v_lshl_or_b32 v178, v15, 13, v177
	v_mov_b32_e32 v14, v1
	v_cndmask_b32_e64 v10, 0, 1, vcc
	v_cmp_ge_u32_e32 vcc, v7, v3
	v_mov_b32_e32 v15, v1
	v_lshl_or_b32 v183, v19, 4, v137
	v_cndmask_b32_e64 v11, 0, 1, vcc
	v_cndmask_b32_e64 v10, v11, v10, s[4:5]
	v_and_b32_e32 v10, 1, v10
	v_cmp_eq_u32_e64 s[16:17], 1, v10
	v_lshrrev_b32_e32 v10, 1, v3
	v_bitop3_b32 v10, v10, v9, 3 bitop3:0x6c
	v_lshlrev_b32_e32 v10, 4, v10
	v_lshl_or_b32 v3, v3, 7, v10
	v_add_u32_e32 v36, 0x14000, v3
	v_or_b32_e32 v3, 8, v0
	v_cmp_le_u32_e32 vcc, v7, v3
	v_mov_b32_e32 v12, v1
	v_mov_b32_e32 v13, v1
	v_cndmask_b32_e64 v10, 0, 1, vcc
	v_cmp_ge_u32_e32 vcc, v7, v3
	v_add_u32_e32 v197, v26, v25
	v_add_u32_e32 v198, v28, v25
	v_cndmask_b32_e64 v11, 0, 1, vcc
	v_cndmask_b32_e64 v10, v11, v10, s[4:5]
	v_and_b32_e32 v10, 1, v10
	v_cmp_eq_u32_e64 s[18:19], 1, v10
	v_lshrrev_b32_e32 v10, 1, v3
	v_bitop3_b32 v10, v10, v9, 6 bitop3:0x6c
	v_lshlrev_b32_e32 v10, 4, v10
	v_lshl_or_b32 v3, v3, 7, v10
	v_add_u32_e32 v38, 0x14000, v3
	v_or_b32_e32 v3, 9, v0
	v_cmp_le_u32_e32 vcc, v7, v3
	v_add_u32_e32 v199, v31, v25
	v_add_u32_e32 v200, v34, v25
	v_cndmask_b32_e64 v10, 0, 1, vcc
	v_cmp_ge_u32_e32 vcc, v7, v3
	v_add_u32_e32 v201, v37, v25
	v_add_u32_e32 v202, v40, v25
	v_cndmask_b32_e64 v11, 0, 1, vcc
	v_cndmask_b32_e64 v10, v11, v10, s[4:5]
	v_and_b32_e32 v10, 1, v10
	v_cmp_eq_u32_e64 s[20:21], 1, v10
	v_lshrrev_b32_e32 v10, 1, v3
	v_bitop3_b32 v10, v10, v9, 6 bitop3:0x6c
	v_lshlrev_b32_e32 v10, 4, v10
	v_lshl_or_b32 v3, v3, 7, v10
	v_add_u32_e32 v39, 0x14000, v3
	v_or_b32_e32 v3, 10, v0
	v_cmp_le_u32_e32 vcc, v7, v3
	v_add_u32_e32 v203, v42, v25
	v_add_u32_e32 v204, v43, v23
	v_cndmask_b32_e64 v10, 0, 1, vcc
	v_cmp_ge_u32_e32 vcc, v7, v3
	v_add_u32_e32 v205, v27, v23
	v_add_u32_e32 v206, v29, v23
	v_cndmask_b32_e64 v11, 0, 1, vcc
	v_cndmask_b32_e64 v10, v11, v10, s[4:5]
	v_and_b32_e32 v10, 1, v10
	v_cmp_eq_u32_e64 s[22:23], 1, v10
	v_lshrrev_b32_e32 v10, 1, v3
	v_bitop3_b32 v10, v10, v9, 7 bitop3:0x6c
	v_lshlrev_b32_e32 v10, 4, v10
	v_lshl_or_b32 v3, v3, 7, v10
	v_add_u32_e32 v41, 0x14000, v3
	v_or_b32_e32 v3, 11, v0
	v_cmp_le_u32_e32 vcc, v7, v3
	v_add_u32_e32 v207, v30, v23
	v_add_u32_e32 v208, v32, v23
	v_cndmask_b32_e64 v10, 0, 1, vcc
	v_cmp_ge_u32_e32 vcc, v7, v3
	v_add_u32_e32 v209, v33, v23
	v_add_u32_e32 v210, v22, v23
	v_cndmask_b32_e64 v11, 0, 1, vcc
	v_cndmask_b32_e64 v10, v11, v10, s[4:5]
	v_and_b32_e32 v10, 1, v10
	v_cmp_eq_u32_e64 s[24:25], 1, v10
	v_lshrrev_b32_e32 v10, 1, v3
	v_bitop3_b32 v10, v10, v9, 7 bitop3:0x6c
	v_lshlrev_b32_e32 v10, 4, v10
	v_lshl_or_b32 v3, v3, 7, v10
	v_add_u32_e32 v44, 0x14000, v3
	v_or_b32_e32 v3, 16, v0
	v_cmp_le_u32_e32 vcc, v7, v3
	v_add_u32_e32 v211, v35, v24
	v_add_u32_e32 v212, v17, v16
	v_cndmask_b32_e64 v10, 0, 1, vcc
	v_cmp_ge_u32_e32 vcc, v7, v3
	v_lshlrev_b32_e32 v3, 7, v3
	v_bitop3_b32 v3, v3, v8, v6 bitop3:0xf6
	v_cndmask_b32_e64 v11, 0, 1, vcc
	v_cndmask_b32_e64 v10, v11, v10, s[4:5]
	v_add_u32_e32 v45, 0x14000, v3
	v_or_b32_e32 v3, 17, v0
	v_and_b32_e32 v10, 1, v10
	v_cmp_le_u32_e32 vcc, v7, v3
	v_cmp_eq_u32_e64 s[26:27], 1, v10
	v_add_u32_e32 v213, v18, v16
	v_cndmask_b32_e64 v10, 0, 1, vcc
	v_cmp_ge_u32_e32 vcc, v7, v3
	v_lshlrev_b32_e32 v3, 7, v3
	v_bitop3_b32 v3, v3, v8, v6 bitop3:0xf6
	v_add_u32_e32 v46, 0x14000, v3
	v_or_b32_e32 v3, 18, v0
	v_cndmask_b32_e64 v11, 0, 1, vcc
	v_cmp_le_u32_e32 vcc, v7, v3
	v_cndmask_b32_e64 v10, v11, v10, s[4:5]
	v_and_b32_e32 v10, 1, v10
	v_cndmask_b32_e64 v6, 0, 1, vcc
	v_cmp_ge_u32_e32 vcc, v7, v3
	v_cmp_eq_u32_e64 s[28:29], 1, v10
	v_mov_b32_e32 v10, v1
	v_cndmask_b32_e64 v8, 0, 1, vcc
	v_cndmask_b32_e64 v6, v8, v6, s[4:5]
	v_and_b32_e32 v6, 1, v6
	v_cmp_eq_u32_e64 s[30:31], 1, v6
	v_lshrrev_b32_e32 v6, 1, v3
	v_bitop3_b32 v6, v6, v9, 3 bitop3:0x6c
	v_lshlrev_b32_e32 v6, 4, v6
	v_lshl_or_b32 v3, v3, 7, v6
	v_add_u32_e32 v47, 0x14000, v3
	v_or_b32_e32 v3, 19, v0
	v_cmp_le_u32_e32 vcc, v7, v3
	v_mov_b32_e32 v11, v1
	v_add_u32_e32 v214, v21, v16
	v_cndmask_b32_e64 v6, 0, 1, vcc
	v_cmp_ge_u32_e32 vcc, v7, v3
	v_add_u32_e32 v215, v36, v16
	v_add_u32_e32 v216, v38, v16
	v_cndmask_b32_e64 v8, 0, 1, vcc
	v_cndmask_b32_e64 v6, v8, v6, s[4:5]
	v_and_b32_e32 v6, 1, v6
	v_cmp_eq_u32_e64 s[34:35], 1, v6
	v_lshrrev_b32_e32 v6, 1, v3
	v_bitop3_b32 v6, v6, v9, 3 bitop3:0x6c
	v_lshlrev_b32_e32 v6, 4, v6
	v_lshl_or_b32 v3, v3, 7, v6
	v_add_u32_e32 v48, 0x14000, v3
	v_or_b32_e32 v3, 24, v0
	v_cmp_le_u32_e32 vcc, v7, v3
	v_add_u32_e32 v217, v39, v16
	v_add_u32_e32 v218, v41, v16
	v_cndmask_b32_e64 v6, 0, 1, vcc
	v_cmp_ge_u32_e32 vcc, v7, v3
	v_add_u32_e32 v219, v44, v16
	v_add_u32_e32 v220, v45, v16
	v_cndmask_b32_e64 v8, 0, 1, vcc
	v_cndmask_b32_e64 v6, v8, v6, s[4:5]
	v_and_b32_e32 v6, 1, v6
	v_cmp_eq_u32_e64 s[36:37], 1, v6
	v_lshrrev_b32_e32 v6, 1, v3
	v_bitop3_b32 v6, v6, v9, 6 bitop3:0x6c
	v_lshlrev_b32_e32 v6, 4, v6
	v_lshl_or_b32 v3, v3, 7, v6
	v_add_u32_e32 v49, 0x14000, v3
	v_or_b32_e32 v3, 25, v0
	v_cmp_le_u32_e32 vcc, v7, v3
	v_add_u32_e32 v221, v46, v16
	v_add_u32_e32 v222, v47, v16
	v_cndmask_b32_e64 v6, 0, 1, vcc
	v_cmp_ge_u32_e32 vcc, v7, v3
	v_add_u32_e32 v223, v48, v16
	v_add_u32_e32 v224, v49, v16
	v_cndmask_b32_e64 v8, 0, 1, vcc
	v_cndmask_b32_e64 v6, v8, v6, s[4:5]
	v_and_b32_e32 v6, 1, v6
	v_cmp_eq_u32_e64 s[38:39], 1, v6
	v_lshrrev_b32_e32 v6, 1, v3
	v_bitop3_b32 v6, v6, v9, 6 bitop3:0x6c
	v_lshlrev_b32_e32 v6, 4, v6
	v_lshl_or_b32 v3, v3, 7, v6
	v_add_u32_e32 v50, 0x14000, v3
	v_or_b32_e32 v3, 26, v0
	v_cmp_le_u32_e32 vcc, v7, v3
	v_or_b32_e32 v0, 27, v0
	v_add_u32_e32 v225, v50, v16
	v_cndmask_b32_e64 v6, 0, 1, vcc
	v_cmp_ge_u32_e32 vcc, v7, v3
	v_or_b32_e32 v182, 0x14000, v181
	s_waitcnt vmcnt(16)
	v_mov_b64_e32 v[170:171], 0
	v_cndmask_b32_e64 v8, 0, 1, vcc
	v_cndmask_b32_e64 v6, v8, v6, s[4:5]
	v_and_b32_e32 v6, 1, v6
	v_cmp_eq_u32_e64 s[40:41], 1, v6
	v_lshrrev_b32_e32 v6, 1, v3
	v_bitop3_b32 v6, v6, v9, 7 bitop3:0x6c
	v_lshlrev_b32_e32 v6, 4, v6
	v_lshl_or_b32 v3, v3, 7, v6
	v_cmp_le_u32_e32 vcc, v7, v0
	v_add_u32_e32 v51, 0x14000, v3
	v_mov_b32_e32 v8, v1
	v_cndmask_b32_e64 v3, 0, 1, vcc
	v_cmp_ge_u32_e32 vcc, v7, v0
	v_mov_b32_e32 v7, v1
	v_add_u32_e32 v226, v51, v16
	v_cndmask_b32_e64 v6, 0, 1, vcc
	v_cndmask_b32_e64 v3, v6, v3, s[4:5]
	v_and_b32_e32 v3, 1, v3
	v_cmp_eq_u32_e64 s[42:43], 1, v3
	v_lshrrev_b32_e32 v3, 1, v0
	v_bitop3_b32 v3, v3, v9, 7 bitop3:0x6c
	v_lshlrev_b32_e32 v3, 4, v3
	v_lshl_or_b32 v0, v0, 7, v3
	v_add_u32_e32 v52, 0x14000, v0
	v_bitop3_b32 v0, v2, v20, 1 bitop3:0x6c
	v_lshlrev_b32_e32 v192, 4, v0
	v_bitop3_b32 v0, v19, v20, 2 bitop3:0x36
	v_lshlrev_b32_e32 v193, 4, v0
	v_bitop3_b32 v0, v19, v20, 4 bitop3:0x36
	v_lshlrev_b32_e32 v195, 4, v0
	v_bitop3_b32 v0, v19, v20, 6 bitop3:0x36
	v_lshlrev_b32_e32 v196, 4, v0
	v_lshlrev_b32_e32 v0, 13, v19
	v_lshl_add_u64 v[168:169], v[4:5], 0, v[0:1]
	v_mov_b32_e32 v0, v1
	v_mov_b32_e32 v2, v1
	v_mov_b32_e32 v3, v1
	v_mov_b32_e32 v4, v1
	v_mov_b32_e32 v5, v1
	v_mov_b32_e32 v6, v1
	v_mov_b32_e32 v9, v1
	v_add_u32_e32 v227, v52, v16
	v_mov_b64_e32 v[30:31], v[14:15]
	v_mov_b64_e32 v[46:47], v[14:15]
	v_mov_b64_e32 v[62:63], v[14:15]
	v_mov_b64_e32 v[78:79], v[14:15]
	s_movk_i32 s89, 0x82
	v_mov_b64_e32 v[28:29], v[12:13]
	v_mov_b64_e32 v[26:27], v[10:11]
	v_mov_b64_e32 v[24:25], v[8:9]
	v_mov_b64_e32 v[22:23], v[6:7]
	v_mov_b64_e32 v[20:21], v[4:5]
	v_mov_b64_e32 v[18:19], v[2:3]
	v_mov_b64_e32 v[16:17], v[0:1]
	v_mov_b64_e32 v[44:45], v[12:13]
	v_mov_b64_e32 v[42:43], v[10:11]
	v_mov_b64_e32 v[40:41], v[8:9]
	v_mov_b64_e32 v[38:39], v[6:7]
	v_mov_b64_e32 v[36:37], v[4:5]
	v_mov_b64_e32 v[34:35], v[2:3]
	v_mov_b64_e32 v[32:33], v[0:1]
	v_mov_b64_e32 v[60:61], v[12:13]
	v_mov_b64_e32 v[58:59], v[10:11]
	v_mov_b64_e32 v[56:57], v[8:9]
	v_mov_b64_e32 v[54:55], v[6:7]
	v_mov_b64_e32 v[52:53], v[4:5]
	v_mov_b64_e32 v[50:51], v[2:3]
	v_mov_b64_e32 v[48:49], v[0:1]
	v_mov_b64_e32 v[76:77], v[12:13]
	v_mov_b64_e32 v[74:75], v[10:11]
	v_mov_b64_e32 v[72:73], v[8:9]
	v_mov_b64_e32 v[70:71], v[6:7]
	v_mov_b64_e32 v[68:69], v[4:5]
	v_mov_b64_e32 v[66:67], v[2:3]
	v_mov_b64_e32 v[64:65], v[0:1]
	s_mov_b32 s81, s49
	v_mov_b64_e32 v[6:7], 0
	v_mov_b64_e32 v[8:9], 0
	v_mov_b64_e32 v[10:11], 0
	v_and_b32_e32 v113, 15, v148
	v_bfe_u32 v114, v148, 5, 1
	v_lshlrev_b32_e32 v115, 2, v113
	v_and_b32_e32 v115, 12, v115
	v_lshrrev_b32_e32 v116, 2, v113
	v_or_b32_e32 v115, v115, v116
	v_xor_b32_e32 v115, v115, v114
	v_xor_b32_e32 v116, 0, v115
	v_lshlrev_b32_e32 v184, 4, v116
	v_xor_b32_e32 v116, 2, v115
	v_lshlrev_b32_e32 v185, 4, v116
	v_xor_b32_e32 v116, 4, v115
	v_lshlrev_b32_e32 v186, 4, v116
	v_xor_b32_e32 v116, 6, v115
	v_lshlrev_b32_e32 v187, 4, v116
	v_xor_b32_e32 v116, 8, v115
	v_lshlrev_b32_e32 v188, 4, v116
	v_xor_b32_e32 v116, 10, v115
	v_lshlrev_b32_e32 v189, 4, v116
	v_xor_b32_e32 v116, 12, v115
	v_lshlrev_b32_e32 v190, 4, v116
	v_xor_b32_e32 v116, 14, v115
	v_lshlrev_b32_e32 v191, 4, v116
	v_lshlrev_b32_e32 v116, 2, v149
	v_and_b32_e32 v116, 12, v116
	v_bfe_u32 v117, v149, 2, 2
	v_or_b32_e32 v116, v116, v117
	v_and_b32_e32 v117, 14, v113
	v_xor_b32_e32 v116, v116, v117
	v_lshlrev_b32_e32 v116, 4, v116
	v_lshl_or_b32 v173, v149, 8, v116
	v_and_b32_e32 v117, 1, v113
	v_lshl_or_b32 v173, v117, 3, v173
	v_xor_b32_e32 v174, 16, v173
	v_mov_b64_e32 v[232:233], 0
	v_mov_b64_e32 v[234:235], 0
	v_and_b32_e32 v116, 3, v148
	v_bfe_u32 v117, v148, 2, 2
	v_bfe_u32 v118, v148, 4, 1
	v_and_b32_e32 v119, 1, v116
	v_lshl_or_b32 v119, v118, 1, v119
	v_lshlrev_b32_e32 v120, 1, v114
	v_xor_b32_e32 v119, v119, v120
	v_lshl_or_b32 v119, v117, 2, v119
	v_lshlrev_b32_e32 v119, 4, v119
	v_lshrrev_b32_e32 v120, 1, v116
	v_lshl_or_b32 v119, v120, 3, v119
	v_lshl_add_u32 v120, v114, 3, v117
	v_lshl_or_b32 v119, v120, 8, v119
	v_add_u32_e32 v197, 0x4000, v119
	v_xor_b32_e32 v198, 64, v197
	v_xor_b32_e32 v199, 0x80, v197
	v_xor_b32_e32 v200, 0xc0, v197
	v_xor_b32_e32 v201, 16, v197
	v_xor_b32_e32 v202, 16, v198
	v_xor_b32_e32 v203, 16, v199
	v_xor_b32_e32 v204, 16, v200
	s_branch .LBB0_1146

.LBB0_1150:
	s_waitcnt vmcnt(4)
	v_cvt_f32_f16_e32 v2, v156
	v_cvt_f32_f16_e32 v0, v142
	v_cvt_f32_f16_sdwa v3, v156 dst_sel:DWORD dst_unused:UNUSED_PAD src0_sel:WORD_1
	v_and_b32_e32 v5, 0xffff0000, v138
	v_exp_f32_e32 v114, v2
	v_exp_f32_e64 v116, -v2
	v_cvt_f32_f16_sdwa v2, v142 dst_sel:DWORD dst_unused:UNUSED_PAD src0_sel:WORD_1
	v_exp_f32_e32 v115, v3
	v_exp_f32_e64 v117, -v3
	v_lshlrev_b32_e32 v4, 16, v138
	v_lshlrev_b32_e32 v14, 16, v8
	v_and_b32_e32 v15, 0xffff0000, v8
	v_pk_mul_f32 v[114:115], v[114:115], v[14:15]
	v_pk_mul_f32 v[116:117], v[116:117], v[4:5]
	v_cvt_f32_f16_e32 v4, v157
	v_cvt_f32_f16_e32 v3, v143
	v_exp_f32_e32 v14, v4
	v_exp_f32_e64 v118, -v4
	v_cvt_f32_f16_sdwa v5, v157 dst_sel:DWORD dst_unused:UNUSED_PAD src0_sel:WORD_1
	v_cvt_f32_f16_sdwa v4, v143 dst_sel:DWORD dst_unused:UNUSED_PAD src0_sel:WORD_1
	v_lshlrev_b32_e32 v12, 16, v139
	v_exp_f32_e32 v15, v5
	v_exp_f32_e64 v119, -v5
	v_and_b32_e32 v13, 0xffff0000, v139
	v_lshlrev_b32_e32 v112, 16, v9
	v_and_b32_e32 v113, 0xffff0000, v9
	v_pk_mul_f32 v[120:121], v[14:15], v[112:113]
	v_pk_mul_f32 v[118:119], v[118:119], v[12:13]
	v_cvt_f32_f16_e32 v12, v158
	v_cvt_f32_f16_e32 v5, v144
	v_cvt_f32_f16_sdwa v13, v158 dst_sel:DWORD dst_unused:UNUSED_PAD src0_sel:WORD_1
	v_lshlrev_b32_e32 v14, 16, v140
	v_exp_f32_e32 v126, v12
	v_exp_f32_e64 v228, -v12
	v_cvt_f32_f16_sdwa v12, v144 dst_sel:DWORD dst_unused:UNUSED_PAD src0_sel:WORD_1
	v_exp_f32_e32 v127, v13
	v_exp_f32_e64 v229, -v13
	v_and_b32_e32 v15, 0xffff0000, v140
	v_lshlrev_b32_e32 v122, 16, v10
	v_and_b32_e32 v123, 0xffff0000, v10
	v_pk_mul_f32 v[122:123], v[126:127], v[122:123]
	v_pk_mul_f32 v[126:127], v[228:229], v[14:15]
	v_cvt_f32_f16_e32 v14, v159
	v_cvt_f32_f16_e32 v13, v145
	v_cvt_f32_f16_sdwa v15, v159 dst_sel:DWORD dst_unused:UNUSED_PAD src0_sel:WORD_1
	v_exp_f32_e32 v228, v14
	v_exp_f32_e64 v230, -v14
	v_cvt_f32_f16_sdwa v14, v145 dst_sel:DWORD dst_unused:UNUSED_PAD src0_sel:WORD_1
	v_exp_f32_e32 v229, v15
	v_exp_f32_e64 v231, -v15
	v_lshlrev_b32_e32 v112, 16, v141
	v_and_b32_e32 v113, 0xffff0000, v141
	v_lshlrev_b32_e32 v124, 16, v11
	v_and_b32_e32 v125, 0xffff0000, v11
	v_pk_mul_f32 v[124:125], v[228:229], v[124:125]
	v_pk_mul_f32 v[228:229], v[230:231], v[112:113]
	v_cvt_pk_bf16_f32 v112, v114, v115
	v_cvt_pk_bf16_f32 v115, v124, v125
	s_waitcnt vmcnt(2)
	v_cvt_f32_f16_e32 v15, v164
	v_cvt_f32_f16_sdwa v124, v164 dst_sel:DWORD dst_unused:UNUSED_PAD src0_sel:WORD_1
	v_cvt_pk_bf16_f32 v114, v122, v123
	v_cvt_pk_bf16_f32 v113, v120, v121
	v_exp_f32_e32 v120, v15
	v_exp_f32_e32 v121, v124
	v_cvt_pk_bf16_f32 v116, v116, v117
	v_cvt_pk_bf16_f32 v117, v118, v119
	v_exp_f32_e64 v122, -v15
	v_cvt_pk_bf16_f32 v118, v126, v127
	v_cvt_pk_bf16_f32 v119, v228, v229
	ds_write_b64 v173, v[112:113] offset:0
	ds_write_b64 v174, v[114:115] offset:0
	ds_write_b64 v173, v[116:117] offset:16384
	ds_write_b64 v174, v[118:119] offset:16384
	v_lshlrev_b32_e32 v116, 16, v232
	v_and_b32_e32 v117, 0xffff0000, v232
	v_pk_mul_f32 v[116:117], v[120:121], v[116:117]
	v_exp_f32_e64 v123, -v124
	v_lshlrev_b32_e32 v112, 16, v160
	v_and_b32_e32 v113, 0xffff0000, v160
	v_pk_mul_f32 v[120:121], v[122:123], v[112:113]
	v_cvt_f32_f16_e32 v123, v165
	v_cvt_f32_f16_sdwa v15, v165 dst_sel:DWORD dst_unused:UNUSED_PAD src0_sel:WORD_1
	v_exp_f32_e32 v112, v123
	v_exp_f32_e64 v122, -v123
	v_exp_f32_e32 v113, v15
	v_exp_f32_e64 v123, -v15
	v_lshlrev_b32_e32 v114, 16, v161
	v_and_b32_e32 v115, 0xffff0000, v161
	v_lshlrev_b32_e32 v118, 16, v233
	v_and_b32_e32 v119, 0xffff0000, v233
	v_pk_mul_f32 v[118:119], v[112:113], v[118:119]
	s_waitcnt vmcnt(2)
	v_cvt_f32_f16_e32 v15, v166
	v_cvt_f32_f16_sdwa v175, v166 dst_sel:DWORD dst_unused:UNUSED_PAD src0_sel:WORD_1
	v_lshlrev_b32_e32 v112, 16, v162
	v_exp_f32_e32 v228, v15
	v_exp_f32_e64 v230, -v15
	v_exp_f32_e32 v229, v175
	v_exp_f32_e64 v231, -v175
	v_and_b32_e32 v113, 0xffff0000, v162
	v_cvt_f32_f16_e32 v175, v167
	v_lshlrev_b32_e32 v124, 16, v234
	v_and_b32_e32 v125, 0xffff0000, v234
	v_pk_mul_f32 v[124:125], v[228:229], v[124:125]
	v_pk_mul_f32 v[228:229], v[230:231], v[112:113]
	v_cvt_f32_f16_sdwa v15, v167 dst_sel:DWORD dst_unused:UNUSED_PAD src0_sel:WORD_1
	v_exp_f32_e32 v112, v175
	v_exp_f32_e64 v230, -v175
	v_cvt_f32_f16_sdwa v194, v145 dst_sel:DWORD dst_unused:UNUSED_PAD src0_sel:WORD_1
	v_exp_f32_e32 v113, v15
	v_exp_f32_e64 v231, -v15
	v_pk_mul_f32 v[122:123], v[122:123], v[114:115]
	v_lshlrev_b32_e32 v114, 16, v163
	v_lshlrev_b32_e32 v126, 16, v235
	v_and_b32_e32 v127, 0xffff0000, v235
	v_and_b32_e32 v115, 0xffff0000, v163
	v_pk_mul_f32 v[126:127], v[112:113], v[126:127]
	v_pk_mul_f32 v[230:231], v[230:231], v[114:115]
	v_cvt_pk_bf16_f32 v112, v116, v117
	v_cvt_pk_bf16_f32 v113, v118, v119
	v_cvt_pk_bf16_f32 v114, v124, v125
	v_cvt_pk_bf16_f32 v115, v126, v127
	v_cvt_pk_bf16_f32 v116, v120, v121
	v_cvt_pk_bf16_f32 v117, v122, v123
	v_cvt_pk_bf16_f32 v118, v228, v229
	v_cvt_pk_bf16_f32 v119, v230, v231
	ds_write_b64 v173, v[112:113] offset:8192
	ds_write_b64 v174, v[114:115] offset:8192
	ds_write_b64 v173, v[116:117] offset:24576
	ds_write_b64 v174, v[118:119] offset:24576
	s_waitcnt vmcnt(1)
	ds_write_b128 v211, v[128:131] offset:49152
	s_waitcnt vmcnt(0)
	ds_write_b128 v211, v[132:135] offset:57344
	s_and_saveexec_b64 s[44:45], s[6:7]
	s_cbranch_execz .LBB0_1152
	v_exp_f32_e32 v112, v0
	v_exp_f32_e32 v113, v2
	v_exp_f32_e32 v114, v3
	v_exp_f32_e32 v115, v4
	v_exp_f32_e32 v2, v5
	v_exp_f32_e32 v3, v12
	v_exp_f32_e32 v4, v13
	v_exp_f32_e32 v5, v14
	v_add_u32_e32 v12, s32, v176
	ds_write_b128 v12, v[112:115]
	ds_write_b128 v12, v[2:5] offset:16

.LBB0_1157:
	v_add_u32_e32 v2, s91, v149
	v_ashrrev_i32_e32 v3, 31, v2
	v_lshlrev_b64 v[2:3], 9, v[2:3]
	v_or_b32_e32 v2, v2, v136
	v_add_u32_e32 v12, s91, v172
	v_ashrrev_i32_e32 v13, 31, v12
	v_lshlrev_b64 v[12:13], 9, v[12:13]
	v_or_b32_e32 v12, v12, v136
	v_mov_b64_e32 v[8:9], 0
	v_mov_b64_e32 v[10:11], 0
	v_mov_b64_e32 v[232:233], 0
	v_mov_b64_e32 v[234:235], 0
	s_andn2_b64 vcc, exec, s[60:61]
	s_cbranch_vccnz .Lscan_noq
	v_lshl_add_u64 v[4:5], v[2:3], 1, s[72:73]
	global_load_dwordx4 v[8:11], v[4:5], off
	v_lshl_add_u64 v[4:5], v[12:13], 1, s[72:73]
	global_load_dwordx4 v[232:235], v[4:5], off
.Lscan_noq:
	v_lshl_add_u64 v[4:5], v[2:3], 1, s[76:77]
	global_load_dwordx4 v[138:141], v[4:5], off
	v_lshl_add_u64 v[4:5], v[2:3], 1, s[70:71]
	global_load_dwordx4 v[156:159], v[4:5], off
	s_add_i32 s60, s91, s86
	s_ashr_i32 s61, s60, 31
	s_lshl_b64 s[60:61], s[60:61], 10
	v_lshl_add_u64 v[4:5], v[146:147], 0, s[60:61]
	global_load_dwordx4 v[142:145], v[4:5], off
	v_lshl_add_u64 v[4:5], v[12:13], 1, s[76:77]
	global_load_dwordx4 v[160:163], v[4:5], off
	v_lshl_add_u64 v[4:5], v[12:13], 1, s[70:71]
	global_load_dwordx4 v[164:167], v[4:5], off
	s_lshl_b64 s[44:45], s[48:49], 1
	v_lshl_add_u64 v[2:3], v[152:153], 0, s[44:45]
	v_lshl_add_u64 v[4:5], v[154:155], 0, s[44:45]
	global_load_dwordx4 v[128:131], v[2:3], off
	global_load_dwordx4 v[132:135], v[4:5], off
	s_cmp_lg_u64 s[8:9], 0
	s_cbranch_scc1 .LBB0_1162
	s_and_b64 vcc, exec, s[82:83]
	s_cbranch_vccnz .Lscan_b2
	s_branch .Lscan_loads_ret
